# overlap final rmsnorm with tail round of out-proj GEMM via arrival counters; out-proj stores agent-scope (sc1) instead of a per-workgroup L2 writeback
# speedup vs baseline: 1.0055x; 1.0055x over previous
.LBB0_983:
	ds_read_b128 v[148:151], v143
	ds_read_b128 v[152:155], v143 offset:1024
	ds_read_b128 v[156:159], v143 offset:2048
	ds_read_b128 v[160:163], v143 offset:3072
	s_add_u32 s22, s20, 0xfffc0080
	s_addc_u32 s23, s21, -1
	s_cmp_eq_u32 s50, 12
	s_cselect_b32 s25, s9, s23
	s_cselect_b32 s24, s46, s22
	s_cselect_b32 s23, s15, s49
	s_cselect_b32 s22, s47, s48
	s_mov_b32 m0, s42
	v_lshl_add_u64 v[196:197], s[20:21], 0, v[134:135]
	ds_read_b128 v[164:167], v142
	ds_read_b128 v[168:171], v142 offset:1024
	ds_read_b128 v[172:175], v142 offset:2048
	ds_read_b128 v[176:179], v142 offset:3072
	ds_read_b128 v[180:183], v142 offset:4096
	ds_read_b128 v[184:187], v142 offset:5120
	ds_read_b128 v[188:191], v142 offset:6144
	ds_read_b128 v[192:195], v142 offset:7168
	global_load_lds_dwordx4 v[196:197], off
	v_lshl_add_u64 v[196:197], s[20:21], 0, v[136:137]
	s_mov_b32 m0, s43
	s_nop 0
	global_load_lds_dwordx4 v[196:197], off
	s_waitcnt lgkmcnt(8)
	s_barrier
	s_waitcnt lgkmcnt(0)
	s_setprio 1
	s_waitcnt lgkmcnt(0)
	v_mfma_f32_16x16x32_bf16 v[124:127], v[148:151], v[164:167], v[124:127]
	v_mfma_f32_16x16x32_bf16 v[120:123], v[156:159], v[164:167], v[120:123]
	v_mfma_f32_16x16x32_bf16 v[116:119], v[148:151], v[172:175], v[116:119]
	v_mfma_f32_16x16x32_bf16 v[112:115], v[156:159], v[172:175], v[112:115]
	v_mfma_f32_16x16x32_bf16 v[108:111], v[148:151], v[180:183], v[108:111]
	v_mfma_f32_16x16x32_bf16 v[104:107], v[156:159], v[180:183], v[104:107]
	v_mfma_f32_16x16x32_bf16 v[100:103], v[148:151], v[188:191], v[100:103]
	v_mfma_f32_16x16x32_bf16 v[96:99], v[156:159], v[188:191], v[96:99]
	v_mfma_f32_16x16x32_bf16 v[124:127], v[152:155], v[168:171], v[124:127]
	v_mfma_f32_16x16x32_bf16 v[120:123], v[160:163], v[168:171], v[120:123]
	v_mfma_f32_16x16x32_bf16 v[116:119], v[152:155], v[176:179], v[116:119]
	v_mfma_f32_16x16x32_bf16 v[112:115], v[160:163], v[176:179], v[112:115]
	v_mfma_f32_16x16x32_bf16 v[108:111], v[152:155], v[184:187], v[108:111]
	v_mfma_f32_16x16x32_bf16 v[104:107], v[160:163], v[184:187], v[104:107]
	v_mfma_f32_16x16x32_bf16 v[100:103], v[152:155], v[192:195], v[100:103]
	v_mfma_f32_16x16x32_bf16 v[96:99], v[160:163], v[192:195], v[96:99]
	s_setprio 0
	s_barrier
	s_mov_b32 m0, s27
	v_lshl_add_u64 v[196:197], s[22:23], 0, v[130:131]
	ds_read_b128 v[200:203], v144
	ds_read_b128 v[204:207], v144 offset:1024
	ds_read_b128 v[208:211], v144 offset:2048
	ds_read_b128 v[212:215], v144 offset:3072
	global_load_lds_dwordx4 v[196:197], off
	v_lshl_add_u64 v[216:217], s[22:23], 0, v[128:129]
	s_mov_b32 m0, s28
	s_nop 0
	global_load_lds_dwordx4 v[216:217], off
	s_barrier
	s_waitcnt lgkmcnt(0)
	s_setprio 1
	s_waitcnt lgkmcnt(0)
	v_mfma_f32_16x16x32_bf16 v[92:95], v[200:203], v[164:167], v[92:95]
	v_mfma_f32_16x16x32_bf16 v[88:91], v[208:211], v[164:167], v[88:91]
	v_mfma_f32_16x16x32_bf16 v[84:87], v[200:203], v[172:175], v[84:87]
	v_mfma_f32_16x16x32_bf16 v[80:83], v[208:211], v[172:175], v[80:83]
	v_mfma_f32_16x16x32_bf16 v[76:79], v[200:203], v[180:183], v[76:79]
	v_mfma_f32_16x16x32_bf16 v[72:75], v[208:211], v[180:183], v[72:75]
	v_mfma_f32_16x16x32_bf16 v[68:71], v[200:203], v[188:191], v[68:71]
	v_mfma_f32_16x16x32_bf16 v[64:67], v[208:211], v[188:191], v[64:67]
	v_mfma_f32_16x16x32_bf16 v[92:95], v[204:207], v[168:171], v[92:95]
	v_mfma_f32_16x16x32_bf16 v[88:91], v[212:215], v[168:171], v[88:91]
	v_mfma_f32_16x16x32_bf16 v[84:87], v[204:207], v[176:179], v[84:87]
	v_mfma_f32_16x16x32_bf16 v[80:83], v[212:215], v[176:179], v[80:83]
	v_mfma_f32_16x16x32_bf16 v[76:79], v[204:207], v[184:187], v[76:79]
	v_mfma_f32_16x16x32_bf16 v[72:75], v[212:215], v[184:187], v[72:75]
	v_mfma_f32_16x16x32_bf16 v[68:71], v[204:207], v[192:195], v[68:71]
	v_mfma_f32_16x16x32_bf16 v[64:67], v[212:215], v[192:195], v[64:67]
	s_setprio 0
	s_mov_b32 m0, s86
	v_lshl_add_u64 v[218:219], s[24:25], 0, v[130:131]
	s_barrier
	ds_read_b128 v[164:167], v142 offset:16384
	ds_read_b128 v[168:171], v142 offset:17408
	ds_read_b128 v[172:175], v142 offset:18432
	ds_read_b128 v[176:179], v142 offset:19456
	ds_read_b128 v[180:183], v142 offset:20480
	ds_read_b128 v[184:187], v142 offset:21504
	ds_read_b128 v[188:191], v142 offset:22528
	ds_read_b128 v[192:195], v142 offset:23552
	global_load_lds_dwordx4 v[218:219], off
	v_lshl_add_u64 v[220:221], s[24:25], 0, v[128:129]
	s_mov_b32 m0, s29
	s_nop 0
	global_load_lds_dwordx4 v[220:221], off
	s_barrier
	s_waitcnt lgkmcnt(0)
	s_setprio 1
	s_waitcnt lgkmcnt(0)
	v_mfma_f32_16x16x32_bf16 v[60:63], v[148:151], v[164:167], v[60:63]
	v_mfma_f32_16x16x32_bf16 v[56:59], v[156:159], v[164:167], v[56:59]
	v_mfma_f32_16x16x32_bf16 v[52:55], v[148:151], v[172:175], v[52:55]
	v_mfma_f32_16x16x32_bf16 v[48:51], v[156:159], v[172:175], v[48:51]
	v_mfma_f32_16x16x32_bf16 v[44:47], v[148:151], v[180:183], v[44:47]
	v_mfma_f32_16x16x32_bf16 v[40:43], v[156:159], v[180:183], v[40:43]
	v_mfma_f32_16x16x32_bf16 v[36:39], v[148:151], v[188:191], v[36:39]
	v_mfma_f32_16x16x32_bf16 v[32:35], v[156:159], v[188:191], v[32:35]
	v_mfma_f32_16x16x32_bf16 v[60:63], v[152:155], v[168:171], v[60:63]
	v_mfma_f32_16x16x32_bf16 v[56:59], v[160:163], v[168:171], v[56:59]
	v_mfma_f32_16x16x32_bf16 v[52:55], v[152:155], v[176:179], v[52:55]
	v_mfma_f32_16x16x32_bf16 v[48:51], v[160:163], v[176:179], v[48:51]
	v_mfma_f32_16x16x32_bf16 v[44:47], v[152:155], v[184:187], v[44:47]
	v_mfma_f32_16x16x32_bf16 v[40:43], v[160:163], v[184:187], v[40:43]
	v_mfma_f32_16x16x32_bf16 v[36:39], v[152:155], v[192:195], v[36:39]
	v_mfma_f32_16x16x32_bf16 v[32:35], v[160:163], v[192:195], v[32:35]
	s_setprio 0
	s_barrier
	s_add_u32 s52, s22, 0x40000
	s_addc_u32 s53, s23, 0
	s_mov_b32 m0, s30
	v_lshl_add_u64 v[148:149], s[52:53], 0, v[130:131]
	global_load_lds_dwordx4 v[148:149], off
	v_lshl_add_u64 v[148:149], s[52:53], 0, v[128:129]
	s_mov_b32 m0, s31
	s_nop 0
	global_load_lds_dwordx4 v[148:149], off
	s_waitcnt vmcnt(6)
	s_barrier
	s_setprio 1
	v_mfma_f32_16x16x32_bf16 v[28:31], v[200:203], v[164:167], v[28:31]
	v_mfma_f32_16x16x32_bf16 v[24:27], v[208:211], v[164:167], v[24:27]
	v_mfma_f32_16x16x32_bf16 v[20:23], v[200:203], v[172:175], v[20:23]
	v_mfma_f32_16x16x32_bf16 v[16:19], v[208:211], v[172:175], v[16:19]
	v_mfma_f32_16x16x32_bf16 v[12:15], v[200:203], v[180:183], v[12:15]
	v_mfma_f32_16x16x32_bf16 v[8:11], v[208:211], v[180:183], v[8:11]
	v_mfma_f32_16x16x32_bf16 v[4:7], v[200:203], v[188:191], v[4:7]
	v_mfma_f32_16x16x32_bf16 v[0:3], v[208:211], v[188:191], v[0:3]
	v_mfma_f32_16x16x32_bf16 v[28:31], v[204:207], v[168:171], v[28:31]
	v_mfma_f32_16x16x32_bf16 v[24:27], v[212:215], v[168:171], v[24:27]
	v_mfma_f32_16x16x32_bf16 v[20:23], v[204:207], v[176:179], v[20:23]
	v_mfma_f32_16x16x32_bf16 v[16:19], v[212:215], v[176:179], v[16:19]
	v_mfma_f32_16x16x32_bf16 v[12:15], v[204:207], v[184:187], v[12:15]
	v_mfma_f32_16x16x32_bf16 v[8:11], v[212:215], v[184:187], v[8:11]
	v_mfma_f32_16x16x32_bf16 v[4:7], v[204:207], v[192:195], v[4:7]
	v_mfma_f32_16x16x32_bf16 v[0:3], v[212:215], v[192:195], v[0:3]
	s_setprio 0
	s_barrier
	ds_read_b128 v[148:151], v145
	ds_read_b128 v[152:155], v145 offset:1024
	ds_read_b128 v[156:159], v145 offset:2048
	ds_read_b128 v[160:163], v145 offset:3072
	s_add_u32 s24, s24, 0x40000
	s_addc_u32 s25, s25, 0
	s_mov_b32 m0, s33
	v_lshl_add_u64 v[200:201], s[24:25], 0, v[130:131]
	ds_read_b128 v[164:167], v142 offset:32768
	ds_read_b128 v[168:171], v142 offset:33792
	ds_read_b128 v[172:175], v142 offset:34816
	ds_read_b128 v[176:179], v142 offset:35840
	ds_read_b128 v[180:183], v142 offset:36864
	ds_read_b128 v[184:187], v142 offset:37888
	ds_read_b128 v[188:191], v142 offset:38912
	ds_read_b128 v[192:195], v142 offset:39936
	global_load_lds_dwordx4 v[200:201], off
	v_lshl_add_u64 v[200:201], s[24:25], 0, v[128:129]
	s_mov_b32 m0, s34
	s_nop 0
	global_load_lds_dwordx4 v[200:201], off
	s_waitcnt lgkmcnt(8)
	s_barrier
	s_waitcnt lgkmcnt(0)
	s_setprio 1
	s_waitcnt lgkmcnt(0)
	v_mfma_f32_16x16x32_bf16 v[124:127], v[148:151], v[164:167], v[124:127]
	v_mfma_f32_16x16x32_bf16 v[120:123], v[156:159], v[164:167], v[120:123]
	v_mfma_f32_16x16x32_bf16 v[116:119], v[148:151], v[172:175], v[116:119]
	v_mfma_f32_16x16x32_bf16 v[112:115], v[156:159], v[172:175], v[112:115]
	v_mfma_f32_16x16x32_bf16 v[108:111], v[148:151], v[180:183], v[108:111]
	v_mfma_f32_16x16x32_bf16 v[104:107], v[156:159], v[180:183], v[104:107]
	v_mfma_f32_16x16x32_bf16 v[100:103], v[148:151], v[188:191], v[100:103]
	v_mfma_f32_16x16x32_bf16 v[96:99], v[156:159], v[188:191], v[96:99]
	v_mfma_f32_16x16x32_bf16 v[124:127], v[152:155], v[168:171], v[124:127]
	v_mfma_f32_16x16x32_bf16 v[120:123], v[160:163], v[168:171], v[120:123]
	v_mfma_f32_16x16x32_bf16 v[116:119], v[152:155], v[176:179], v[116:119]
	v_mfma_f32_16x16x32_bf16 v[112:115], v[160:163], v[176:179], v[112:115]
	v_mfma_f32_16x16x32_bf16 v[108:111], v[152:155], v[184:187], v[108:111]
	v_mfma_f32_16x16x32_bf16 v[104:107], v[160:163], v[184:187], v[104:107]
	v_mfma_f32_16x16x32_bf16 v[100:103], v[152:155], v[192:195], v[100:103]
	v_mfma_f32_16x16x32_bf16 v[96:99], v[160:163], v[192:195], v[96:99]
	s_setprio 0
	s_barrier
	s_mov_b32 m0, s36
	v_lshl_add_u64 v[196:197], v[196:197], 0, s[6:7]
	ds_read_b128 v[200:203], v146
	ds_read_b128 v[204:207], v146 offset:1024
	ds_read_b128 v[208:211], v146 offset:2048
	ds_read_b128 v[212:215], v146 offset:3072
	global_load_lds_dwordx4 v[196:197], off
	v_lshl_add_u64 v[196:197], v[216:217], 0, s[6:7]
	s_mov_b32 m0, s37
	s_nop 0
	global_load_lds_dwordx4 v[196:197], off
	s_barrier
	s_waitcnt lgkmcnt(0)
	s_setprio 1
	s_waitcnt lgkmcnt(0)
	v_mfma_f32_16x16x32_bf16 v[92:95], v[200:203], v[164:167], v[92:95]
	v_mfma_f32_16x16x32_bf16 v[88:91], v[208:211], v[164:167], v[88:91]
	v_mfma_f32_16x16x32_bf16 v[84:87], v[200:203], v[172:175], v[84:87]
	v_mfma_f32_16x16x32_bf16 v[80:83], v[208:211], v[172:175], v[80:83]
	v_mfma_f32_16x16x32_bf16 v[76:79], v[200:203], v[180:183], v[76:79]
	v_mfma_f32_16x16x32_bf16 v[72:75], v[208:211], v[180:183], v[72:75]
	v_mfma_f32_16x16x32_bf16 v[68:71], v[200:203], v[188:191], v[68:71]
	v_mfma_f32_16x16x32_bf16 v[64:67], v[208:211], v[188:191], v[64:67]
	v_mfma_f32_16x16x32_bf16 v[92:95], v[204:207], v[168:171], v[92:95]
	v_mfma_f32_16x16x32_bf16 v[88:91], v[212:215], v[168:171], v[88:91]
	v_mfma_f32_16x16x32_bf16 v[84:87], v[204:207], v[176:179], v[84:87]
	v_mfma_f32_16x16x32_bf16 v[80:83], v[212:215], v[176:179], v[80:83]
	v_mfma_f32_16x16x32_bf16 v[76:79], v[204:207], v[184:187], v[76:79]
	v_mfma_f32_16x16x32_bf16 v[72:75], v[212:215], v[184:187], v[72:75]
	v_mfma_f32_16x16x32_bf16 v[68:71], v[204:207], v[192:195], v[68:71]
	v_mfma_f32_16x16x32_bf16 v[64:67], v[212:215], v[192:195], v[64:67]
	s_setprio 0
	s_mov_b32 m0, s38
	v_lshl_add_u64 v[196:197], v[218:219], 0, s[6:7]
	s_barrier
	ds_read_b128 v[164:167], v142 offset:49152
	ds_read_b128 v[168:171], v142 offset:50176
	ds_read_b128 v[172:175], v142 offset:51200
	ds_read_b128 v[176:179], v142 offset:52224
	ds_read_b128 v[180:183], v142 offset:53248
	ds_read_b128 v[184:187], v142 offset:54272
	ds_read_b128 v[188:191], v142 offset:55296
	ds_read_b128 v[192:195], v142 offset:56320
	global_load_lds_dwordx4 v[196:197], off
	v_lshl_add_u64 v[196:197], v[220:221], 0, s[6:7]
	s_mov_b32 m0, s39
	s_nop 0
	global_load_lds_dwordx4 v[196:197], off
	s_barrier
	s_waitcnt lgkmcnt(0)
	s_setprio 1
	s_waitcnt lgkmcnt(0)
	v_mfma_f32_16x16x32_bf16 v[60:63], v[148:151], v[164:167], v[60:63]
	v_mfma_f32_16x16x32_bf16 v[56:59], v[156:159], v[164:167], v[56:59]
	v_mfma_f32_16x16x32_bf16 v[52:55], v[148:151], v[172:175], v[52:55]
	v_mfma_f32_16x16x32_bf16 v[48:51], v[156:159], v[172:175], v[48:51]
	v_mfma_f32_16x16x32_bf16 v[44:47], v[148:151], v[180:183], v[44:47]
	v_mfma_f32_16x16x32_bf16 v[40:43], v[156:159], v[180:183], v[40:43]
	v_mfma_f32_16x16x32_bf16 v[36:39], v[148:151], v[188:191], v[36:39]
	v_mfma_f32_16x16x32_bf16 v[32:35], v[156:159], v[188:191], v[32:35]
	v_mfma_f32_16x16x32_bf16 v[60:63], v[152:155], v[168:171], v[60:63]
	v_mfma_f32_16x16x32_bf16 v[56:59], v[160:163], v[168:171], v[56:59]
	v_mfma_f32_16x16x32_bf16 v[52:55], v[152:155], v[176:179], v[52:55]
	v_mfma_f32_16x16x32_bf16 v[48:51], v[160:163], v[176:179], v[48:51]
	v_mfma_f32_16x16x32_bf16 v[44:47], v[152:155], v[184:187], v[44:47]
	v_mfma_f32_16x16x32_bf16 v[40:43], v[160:163], v[184:187], v[40:43]
	v_mfma_f32_16x16x32_bf16 v[36:39], v[152:155], v[192:195], v[36:39]
	v_mfma_f32_16x16x32_bf16 v[32:35], v[160:163], v[192:195], v[32:35]
	s_setprio 0
	s_barrier
	s_add_u32 s22, s22, 0x40080
	s_addc_u32 s23, s23, 0
	s_mov_b32 m0, s40
	v_lshl_add_u64 v[148:149], s[22:23], 0, v[130:131]
	global_load_lds_dwordx4 v[148:149], off
	v_lshl_add_u64 v[148:149], s[22:23], 0, v[128:129]
	s_mov_b32 m0, s41
	s_nop 0
	global_load_lds_dwordx4 v[148:149], off
	s_waitcnt vmcnt(6)
	s_barrier
	s_setprio 1
	v_mfma_f32_16x16x32_bf16 v[28:31], v[200:203], v[164:167], v[28:31]
	v_mfma_f32_16x16x32_bf16 v[24:27], v[208:211], v[164:167], v[24:27]
	v_mfma_f32_16x16x32_bf16 v[20:23], v[200:203], v[172:175], v[20:23]
	v_mfma_f32_16x16x32_bf16 v[16:19], v[208:211], v[172:175], v[16:19]
	v_mfma_f32_16x16x32_bf16 v[12:15], v[200:203], v[180:183], v[12:15]
	v_mfma_f32_16x16x32_bf16 v[8:11], v[208:211], v[180:183], v[8:11]
	v_mfma_f32_16x16x32_bf16 v[4:7], v[200:203], v[188:191], v[4:7]
	v_mfma_f32_16x16x32_bf16 v[0:3], v[208:211], v[188:191], v[0:3]
	v_mfma_f32_16x16x32_bf16 v[28:31], v[204:207], v[168:171], v[28:31]
	v_mfma_f32_16x16x32_bf16 v[24:27], v[212:215], v[168:171], v[24:27]
	v_mfma_f32_16x16x32_bf16 v[20:23], v[204:207], v[176:179], v[20:23]
	v_mfma_f32_16x16x32_bf16 v[16:19], v[212:215], v[176:179], v[16:19]
	v_mfma_f32_16x16x32_bf16 v[12:15], v[204:207], v[184:187], v[12:15]
	v_mfma_f32_16x16x32_bf16 v[8:11], v[212:215], v[184:187], v[8:11]
	v_mfma_f32_16x16x32_bf16 v[4:7], v[204:207], v[192:195], v[4:7]
	v_mfma_f32_16x16x32_bf16 v[0:3], v[212:215], v[192:195], v[0:3]
	s_setprio 0
	s_add_i32 s50, s50, 2
	s_add_u32 s20, s20, 0x100
	s_addc_u32 s21, s21, 0
	s_add_u32 s48, s48, 0x100
	s_addc_u32 s49, s49, 0
	s_cmp_gt_u32 s50, 13
	s_barrier
	s_cbranch_scc0 .LBB0_983
	v_mov_b32_e32 v147, v198
	v_readlane_b32 s9, v252, 43
	v_readlane_b32 s15, v252, 45
	v_cvt_pk_bf16_f32 v124, v124, v125
	v_ashrrev_i32_e32 v149, 4, v147
	v_and_b32_e32 v132, 15, v147
	v_lshl_add_u32 v156, s9, 4, v149
	s_lshl_b32 s9, s9, 6
	v_lshlrev_b32_e32 v161, 8, v132
	v_lshlrev_b32_e32 v148, 4, v132
	v_lshl_add_u32 v132, v149, 3, s9
	v_xor_b32_e32 v162, v132, v148
	v_add_u32_e32 v132, 32, v132
	v_xor_b32_e32 v163, v132, v148
	v_xor_b32_e32 v132, v149, v147
	v_lshlrev_b32_e32 v132, 4, v132
	v_add_u32_e32 v149, 4, v156
	v_add_u32_e32 v160, 8, v156
	v_cvt_pk_bf16_f32 v125, v126, v127
	v_add3_u32 v126, s35, v162, v161
	v_cvt_pk_bf16_f32 v120, v120, v121
	v_cvt_pk_bf16_f32 v121, v122, v123
	v_add3_u32 v122, s35, v163, v161
	v_cvt_pk_bf16_f32 v116, v116, v117
	v_cvt_pk_bf16_f32 v117, v118, v119
	v_cvt_pk_bf16_f32 v112, v112, v113
	v_cvt_pk_bf16_f32 v113, v114, v115
	v_cvt_pk_bf16_f32 v108, v108, v109
	v_cvt_pk_bf16_f32 v109, v110, v111
	v_cvt_pk_bf16_f32 v104, v104, v105
	v_cvt_pk_bf16_f32 v105, v106, v107
	v_cvt_pk_bf16_f32 v100, v100, v101
	v_cvt_pk_bf16_f32 v101, v102, v103
	v_cvt_pk_bf16_f32 v96, v96, v97
	v_cvt_pk_bf16_f32 v97, v98, v99
	s_lshl_b32 s20, s4, 8
	s_lshl_b32 s15, s15, 6
	v_lshlrev_b32_e32 v164, 8, v156
	v_and_b32_e32 v165, 0xf0, v132
	v_xor_b32_e32 v150, v149, v147
	v_xor_b32_e32 v152, v160, v147
	ds_write_b64 v126, v[124:125]
	ds_write_b64 v122, v[120:121]
	ds_write_b64 v126, v[116:117] offset:4096
	ds_write_b64 v122, v[112:113] offset:4096
	ds_write_b64 v126, v[108:109] offset:8192
	ds_write_b64 v122, v[104:105] offset:8192
	ds_write_b64 v126, v[100:101] offset:12288
	ds_write_b64 v122, v[96:97] offset:12288
	s_add_i32 s15, s15, s20
	v_lshlrev_b32_e32 v150, 4, v150
	v_lshlrev_b32_e32 v152, 4, v152
	v_add_u32_e32 v170, 12, v156
	s_waitcnt lgkmcnt(0)
	s_barrier
	v_add3_u32 v114, s35, v165, v164
	v_add_lshl_u32 v132, s15, v156, 10
	v_and_b32_e32 v167, 0xf0, v150
	v_add_lshl_u32 v150, v149, s15, 10
	v_and_b32_e32 v169, 0xf0, v152
	v_add_lshl_u32 v152, v160, s15, 10
	v_add_lshl_u32 v154, v170, s15, 10
	s_addk_i32 s15, 0x80
	ds_read_b128 v[96:99], v114
	v_lshlrev_b32_e32 v166, 8, v149
	v_add_lshl_u32 v158, s15, v149, 10
	v_mov_b32_e32 v149, v133
	s_lshl_b32 s4, s45, 8
	v_xor_b32_e32 v147, v170, v147
	v_lshl_add_u64 v[148:149], s[10:11], 0, v[148:149]
	v_lshlrev_b32_e32 v168, 8, v160
	v_lshlrev_b32_e32 v147, 4, v147
	v_lshl_add_u64 v[108:109], s[4:5], 1, v[148:149]
	v_add3_u32 v115, s35, v167, v166
	v_lshlrev_b32_e32 v171, 8, v170
	v_and_b32_e32 v147, 0xf0, v147
	v_lshl_add_u64 v[110:111], v[132:133], 1, v[108:109]
	ds_read_b128 v[100:103], v115
	v_add3_u32 v116, s35, v169, v168
	s_waitcnt lgkmcnt(0)
	global_store_dwordx4 v[110:111], v[96:99], off sc1
	ds_read_b128 v[96:99], v116
	v_add3_u32 v117, s35, v147, v171
	ds_read_b128 v[104:107], v117
	v_mov_b32_e32 v151, v133
	v_mov_b32_e32 v153, v133
	v_lshl_add_u64 v[112:113], v[150:151], 1, v[108:109]
	v_mov_b32_e32 v155, v133
	global_store_dwordx4 v[112:113], v[100:103], off sc1
	v_cvt_pk_bf16_f32 v92, v92, v93
	v_cvt_pk_bf16_f32 v93, v94, v95
	v_lshl_add_u64 v[100:101], v[152:153], 1, v[108:109]
	s_waitcnt lgkmcnt(0)
	global_store_dwordx4 v[100:101], v[96:99], off sc1
	v_cvt_pk_bf16_f32 v88, v88, v89
	v_cvt_pk_bf16_f32 v89, v90, v91
	v_lshl_add_u64 v[96:97], v[154:155], 1, v[108:109]
	global_store_dwordx4 v[96:97], v[104:107], off sc1
	v_cvt_pk_bf16_f32 v84, v84, v85
	v_cvt_pk_bf16_f32 v85, v86, v87
	v_cvt_pk_bf16_f32 v80, v80, v81
	v_cvt_pk_bf16_f32 v81, v82, v83
	v_cvt_pk_bf16_f32 v76, v76, v77
	v_cvt_pk_bf16_f32 v77, v78, v79
	v_cvt_pk_bf16_f32 v72, v72, v73
	v_cvt_pk_bf16_f32 v73, v74, v75
	v_cvt_pk_bf16_f32 v68, v68, v69
	v_cvt_pk_bf16_f32 v69, v70, v71
	v_cvt_pk_bf16_f32 v64, v64, v65
	v_cvt_pk_bf16_f32 v65, v66, v67
	s_waitcnt lgkmcnt(0)
	s_barrier
	ds_write_b64 v126, v[92:93]
	ds_write_b64 v122, v[88:89]
	ds_write_b64 v126, v[84:85] offset:4096
	ds_write_b64 v122, v[80:81] offset:4096
	ds_write_b64 v126, v[76:77] offset:8192
	ds_write_b64 v122, v[72:73] offset:8192
	ds_write_b64 v126, v[68:69] offset:12288
	ds_write_b64 v122, v[64:65] offset:12288
	s_waitcnt lgkmcnt(0)
	s_barrier
	ds_read_b128 v[64:67], v114
	ds_read_b128 v[68:71], v115
	ds_read_b128 v[72:75], v116
	ds_read_b128 v[76:79], v117
	s_waitcnt lgkmcnt(0)
	global_store_dwordx4 v[110:111], v[64:67], off offset:256 sc1
	global_store_dwordx4 v[112:113], v[68:71], off offset:256 sc1
	global_store_dwordx4 v[100:101], v[72:75], off offset:256 sc1
	global_store_dwordx4 v[96:97], v[76:79], off offset:256 sc1
	v_cvt_pk_bf16_f32 v60, v60, v61
	v_cvt_pk_bf16_f32 v61, v62, v63
	v_cvt_pk_bf16_f32 v56, v56, v57
	v_cvt_pk_bf16_f32 v57, v58, v59
	v_cvt_pk_bf16_f32 v52, v52, v53
	v_cvt_pk_bf16_f32 v53, v54, v55
	v_cvt_pk_bf16_f32 v48, v48, v49
	v_cvt_pk_bf16_f32 v49, v50, v51
	v_cvt_pk_bf16_f32 v44, v44, v45
	v_cvt_pk_bf16_f32 v45, v46, v47
	v_cvt_pk_bf16_f32 v40, v40, v41
	v_cvt_pk_bf16_f32 v41, v42, v43
	v_cvt_pk_bf16_f32 v36, v36, v37
	v_cvt_pk_bf16_f32 v37, v38, v39
	v_cvt_pk_bf16_f32 v32, v32, v33
	v_cvt_pk_bf16_f32 v33, v34, v35
	s_waitcnt lgkmcnt(0)
	s_barrier
	ds_write_b64 v126, v[60:61]
	ds_write_b64 v122, v[56:57]
	ds_write_b64 v126, v[52:53] offset:4096
	ds_write_b64 v122, v[48:49] offset:4096
	ds_write_b64 v126, v[44:45] offset:8192
	ds_write_b64 v122, v[40:41] offset:8192
	ds_write_b64 v126, v[36:37] offset:12288
	ds_write_b64 v122, v[32:33] offset:12288
	s_waitcnt lgkmcnt(0)
	s_barrier
	ds_read_b128 v[32:35], v114
	ds_read_b128 v[36:39], v115
	v_add_lshl_u32 v156, s15, v156, 10
	v_mov_b32_e32 v157, v133
	v_lshl_add_u64 v[46:47], v[156:157], 1, v[108:109]
	s_waitcnt lgkmcnt(0)
	global_store_dwordx4 v[46:47], v[32:35], off sc1
	ds_read_b128 v[32:35], v116
	ds_read_b128 v[40:43], v117
	v_mov_b32_e32 v159, v133
	v_add_lshl_u32 v160, s15, v160, 10
	v_mov_b32_e32 v161, v133
	v_lshl_add_u64 v[48:49], v[158:159], 1, v[108:109]
	v_add_lshl_u32 v44, s15, v170, 10
	v_mov_b32_e32 v45, v133
	global_store_dwordx4 v[48:49], v[36:39], off sc1
	v_cvt_pk_bf16_f32 v28, v28, v29
	v_cvt_pk_bf16_f32 v29, v30, v31
	v_lshl_add_u64 v[36:37], v[160:161], 1, v[108:109]
	s_waitcnt lgkmcnt(0)
	global_store_dwordx4 v[36:37], v[32:35], off sc1
	v_cvt_pk_bf16_f32 v24, v24, v25
	v_cvt_pk_bf16_f32 v25, v26, v27
	v_lshl_add_u64 v[32:33], v[44:45], 1, v[108:109]
	global_store_dwordx4 v[32:33], v[40:43], off sc1
	v_cvt_pk_bf16_f32 v20, v20, v21
	v_cvt_pk_bf16_f32 v21, v22, v23
	v_cvt_pk_bf16_f32 v16, v16, v17
	v_cvt_pk_bf16_f32 v17, v18, v19
	v_cvt_pk_bf16_f32 v12, v12, v13
	v_cvt_pk_bf16_f32 v13, v14, v15
	v_cvt_pk_bf16_f32 v8, v8, v9
	v_cvt_pk_bf16_f32 v9, v10, v11
	v_cvt_pk_bf16_f32 v4, v4, v5
	v_cvt_pk_bf16_f32 v5, v6, v7
	v_cvt_pk_bf16_f32 v0, v0, v1
	v_cvt_pk_bf16_f32 v1, v2, v3
	s_waitcnt lgkmcnt(0)
	s_barrier
	ds_write_b64 v126, v[28:29]
	ds_write_b64 v122, v[24:25]
	ds_write_b64 v126, v[20:21] offset:4096
	ds_write_b64 v122, v[16:17] offset:4096
	ds_write_b64 v126, v[12:13] offset:8192
	ds_write_b64 v122, v[8:9] offset:8192
	ds_write_b64 v126, v[4:5] offset:12288
	ds_write_b64 v122, v[0:1] offset:12288
	s_waitcnt lgkmcnt(0)
	s_barrier
	ds_read_b128 v[0:3], v114
	ds_read_b128 v[4:7], v115
	ds_read_b128 v[8:11], v116
	ds_read_b128 v[12:15], v117
	s_waitcnt lgkmcnt(0)
	global_store_dwordx4 v[46:47], v[0:3], off offset:256 sc1
	global_store_dwordx4 v[48:49], v[4:7], off offset:256 sc1
	global_store_dwordx4 v[36:37], v[8:11], off offset:256 sc1
	global_store_dwordx4 v[32:33], v[12:15], off offset:256 sc1
	s_waitcnt lgkmcnt(0)
	s_barrier
	s_cmp_lt_u32 s44, 2
	s_cbranch_scc1 .Lp5_nosig
	s_waitcnt vmcnt(0)
	s_barrier
	s_barrier
	v_readlane_b32 s98, v252, 35
	v_readlane_b32 s99, v252, 36
	s_and_b64 vcc, exec, s[98:99]
	s_cbranch_vccnz .Lp5_nosig
	s_nop 0
	s_waitcnt vmcnt(0)
	v_readlane_b32 s100, v252, 25
	v_readlane_b32 s101, v252, 26
	s_cmp_eq_u32 s44, 2
	s_movk_i32 s98, 0x300
	s_cselect_b32 s98, 0x100, s98
	v_mov_b32_e32 v254, s98
	v_mov_b32_e32 v255, 1
	s_mov_b64 s[98:99], exec
	s_mov_b64 exec, 1
	s_nop 1
	global_atomic_add v254, v255, s[100:101]
	s_waitcnt vmcnt(0)
	s_mov_b64 exec, s[98:99]
.Lp5_nosig:
	s_and_b64 vcc, exec, s[0:1]
	s_mov_b32 s45, s14
	s_mov_b32 s4, s8
	s_mov_b64 s[22:23], s[18:19]
	s_mov_b64 s[20:21], s[16:17]
	s_cbranch_vccz .LBB0_980
	v_readlane_b32 s0, v252, 59
	s_waitcnt vmcnt(0)
	v_readlane_b32 s1, v252, 60
	s_andn2_b64 vcc, exec, s[0:1]
	s_cbranch_vccnz .LBB0_987
	s_barrier

.LBB0_988:
	s_waitcnt vmcnt(0)
	v_readlane_b32 s0, v252, 35
	v_readlane_b32 s1, v252, 36
	s_and_b64 vcc, exec, s[0:1]
	s_waitcnt vmcnt(0)
	s_barrier
	s_cbranch_vccnz .LBB0_1049
	v_readlane_b32 s2, v252, 25
	v_readlane_b32 s3, v252, 26
	v_mov_b32_e32 v0, 0
	s_mov_b32 s9, 0
	s_nop 2
.Lp6_pollA:
	global_load_dword v1, v0, s[2:3] offset:256 sc1
	s_waitcnt vmcnt(0)
	v_readfirstlane_b32 s4, v1
	s_cmp_ge_u32 s4, 0x100
	s_cbranch_scc1 .Lp6_gotA
	s_sleep 2
	s_add_i32 s9, s9, 1
	s_cmp_lt_u32 s9, 0x8000
	s_cbranch_scc1 .Lp6_pollA
.Lp6_gotA:
	buffer_inv sc1
	s_waitcnt vmcnt(0)
.LBB0_1049:
	s_barrier
	s_mov_b32 s98, 0
	v_readlane_b32 s0, v252, 17
	s_mov_b32 s101, -1
	s_nop 2
	s_lshr_b32 s1, s0, 13
	s_add_i32 s100, s1, 1
	s_cmp_lt_u32 s1, 7
	s_cselect_b32 s100, s100, -1
	s_cmp_eq_u32 s1, 1
	s_cselect_b32 s101, 8, -1
.Lp6_pass:
	v_readlane_b32 s0, v252, 17
	s_mov_b32 s99, 0
	s_nop 0
	v_add_u32_e32 v0, s0, v240
	v_ashrrev_i32_e32 v0, 5, v0
	v_and_b32_e32 v16, -2, v0
	s_mov_b32 s0, 0x8200
	v_cmp_gt_i32_e32 vcc, s0, v16
	s_and_saveexec_b64 s[0:1], vcc
	s_xor_b64 s[0:1], exec, s[0:1]
	s_cbranch_execz .LBB0_1052
	v_ashrrev_i32_e32 v17, 31, v16
	v_lshlrev_b64 v[2:3], 12, v[16:17]
	v_and_b32_e32 v1, 63, v240
	v_lshl_or_b32 v2, v1, 4, v2
	v_lshl_add_u64 v[2:3], s[74:75], 0, v[2:3]
	s_mov_b64 s[0:1], 0x1000
	v_lshlrev_b32_e32 v0, 2, v240
	v_lshl_add_u64 v[22:23], v[2:3], 0, s[0:1]
	v_lshlrev_b64 v[2:3], 11, v[16:17]
	v_and_b32_e32 v0, 0xfc, v0
	s_lshl_b32 s0, s90, 4
	v_lshl_or_b32 v2, v1, 3, v2
	v_mov_b32_e32 v19, 0
	v_lshlrev_b32_e32 v18, 2, v0
	s_bfe_i32 s3, s0, 0x1001a
	s_bfe_i32 s2, s0, 0x1b0000
	v_lshl_add_u64 v[2:3], s[88:89], 0, v[2:3]
	s_mov_b64 s[0:1], 0x12e80e00
	s_ashr_i32 s11, s96, 5
	v_lshl_add_u64 v[20:21], s[72:73], 0, v[18:19]
	s_lshl_b64 s[4:5], s[2:3], 12
	v_lshl_add_u64 v[24:25], v[2:3], 0, s[0:1]
	s_lshl_b64 s[6:7], s[2:3], 11
	v_lshl_add_u64 v[26:27], v[16:17], 0, 1
	s_mov_b64 s[8:9], 0
	s_mov_b32 s12, 0x8000
	v_mov_b32_e32 v17, s59
	v_mov_b32_e32 v29, s57
	v_mov_b32_e32 v50, s58
	v_mov_b32_e32 v51, s56
	v_lshlrev_b32_e32 v18, 2, v0
	s_mov_b32 s10, 0x3a800000
	v_mov_b32_e32 v28, 0x358637bd
	s_mov_b32 s13, 0x800000
	s_mov_b32 s14, 0x81ff
.LBB0_1051:
	s_cmp_eq_u32 s99, s100
	s_cselect_b32 s0, 1, 0
	s_cmp_eq_u32 s99, s101
	s_cselect_b32 s1, 1, 0
	s_or_b32 s0, s0, s1
	s_add_i32 s99, s99, 1
	s_cmp_lg_u32 s0, s98
	s_cbranch_scc1 .Lp6_skip
	v_lshl_add_u64 v[46:47], v[26:27], 0, -1
	v_cmp_gt_i32_e32 vcc, s12, v16
	v_add_u32_e32 v48, 0xffff8000, v16
	v_add_u32_e32 v54, 0xffff8001, v16
	v_cmp_gt_i32_e64 s[0:1], s12, v26
	v_cndmask_b32_e32 v47, 0, v47, vcc
	v_cndmask_b32_e32 v46, v48, v46, vcc
	v_cndmask_b32_e64 v49, 0, v27, s[0:1]
	v_cndmask_b32_e32 v53, v17, v29, vcc
	v_cndmask_b32_e32 v52, v50, v51, vcc
	v_cndmask_b32_e64 v48, v54, v26, s[0:1]
	v_lshlrev_b64 v[46:47], 12, v[46:47]
	global_load_dwordx2 v[36:37], v[24:25], off offset:-3584 nt
	global_load_dwordx2 v[34:35], v[24:25], off offset:-3072 nt
	global_load_dwordx2 v[32:33], v[24:25], off offset:-2560 nt
	global_load_dwordx2 v[30:31], v[24:25], off offset:-2048 nt
	v_cndmask_b32_e64 v55, v17, v29, s[0:1]
	v_cndmask_b32_e64 v54, v50, v51, s[0:1]
	v_lshlrev_b64 v[48:49], 12, v[48:49]
	v_lshl_add_u64 v[46:47], v[52:53], 0, v[46:47]
	v_lshl_add_u64 v[48:49], v[54:55], 0, v[48:49]
	v_lshl_add_u64 v[80:81], v[46:47], 0, v[18:19]
	global_load_dwordx2 v[44:45], v[24:25], off offset:-1536 nt
	global_load_dwordx2 v[42:43], v[24:25], off offset:-1024 nt
	global_load_dwordx2 v[40:41], v[24:25], off offset:-512 nt
	global_load_dwordx2 v[38:39], v[24:25], off nt
	global_load_dwordx4 v[12:15], v[20:21], off
	global_load_dwordx4 v[8:11], v[20:21], off offset:1024
	global_load_dwordx4 v[4:7], v[20:21], off offset:2048
	global_load_dwordx4 v[0:3], v[20:21], off offset:3072
	v_lshl_add_u64 v[82:83], v[48:49], 0, v[18:19]
	global_load_dwordx4 v[46:49], v[80:81], off nt
	global_load_dwordx4 v[52:55], v[80:81], off offset:1024 nt
	global_load_dwordx4 v[56:59], v[80:81], off offset:2048 nt
	global_load_dwordx4 v[60:63], v[80:81], off offset:3072 nt
	global_load_dwordx4 v[64:67], v[82:83], off nt
	global_load_dwordx4 v[68:71], v[82:83], off offset:1024 nt
	global_load_dwordx4 v[72:75], v[82:83], off offset:2048 nt
	global_load_dwordx4 v[76:79], v[82:83], off offset:3072 nt
	v_add_u32_e32 v16, s11, v16
	v_cmp_lt_i32_e32 vcc, s14, v16
	s_or_b64 s[8:9], vcc, s[8:9]
	v_lshl_add_u64 v[24:25], v[24:25], 0, s[6:7]
	v_lshl_add_u64 v[26:27], v[26:27], 0, s[2:3]
	s_waitcnt vmcnt(19)
	v_and_b32_e32 v81, 0xffff0000, v36
	v_lshlrev_b32_e32 v80, 16, v36
	v_and_b32_e32 v83, 0xffff0000, v37
	v_lshlrev_b32_e32 v82, 16, v37
	s_waitcnt vmcnt(18)
	v_and_b32_e32 v37, 0xffff0000, v34
	v_lshlrev_b32_e32 v36, 16, v34
	v_and_b32_e32 v85, 0xffff0000, v35
	v_lshlrev_b32_e32 v84, 16, v35
	s_waitcnt vmcnt(17)
	v_and_b32_e32 v35, 0xffff0000, v32
	v_lshlrev_b32_e32 v34, 16, v32
	v_and_b32_e32 v87, 0xffff0000, v33
	v_lshlrev_b32_e32 v86, 16, v33
	s_waitcnt vmcnt(16)
	v_and_b32_e32 v33, 0xffff0000, v30
	v_lshlrev_b32_e32 v32, 16, v30
	v_and_b32_e32 v89, 0xffff0000, v31
	v_lshlrev_b32_e32 v88, 16, v31
	s_waitcnt vmcnt(15)
	v_and_b32_e32 v31, 0xffff0000, v44
	v_lshlrev_b32_e32 v30, 16, v44
	v_and_b32_e32 v91, 0xffff0000, v45
	v_lshlrev_b32_e32 v90, 16, v45
	s_waitcnt vmcnt(14)
	v_and_b32_e32 v45, 0xffff0000, v42
	v_lshlrev_b32_e32 v44, 16, v42
	v_and_b32_e32 v93, 0xffff0000, v43
	v_lshlrev_b32_e32 v92, 16, v43
	s_waitcnt vmcnt(13)
	v_and_b32_e32 v43, 0xffff0000, v40
	v_lshlrev_b32_e32 v42, 16, v40
	v_and_b32_e32 v95, 0xffff0000, v41
	v_lshlrev_b32_e32 v94, 16, v41
	s_waitcnt vmcnt(12)
	v_and_b32_e32 v41, 0xffff0000, v38
	v_lshlrev_b32_e32 v40, 16, v38
	v_and_b32_e32 v97, 0xffff0000, v39
	v_lshlrev_b32_e32 v96, 16, v39
	s_waitcnt vmcnt(7)
	v_pk_add_f32 v[38:39], v[46:47], v[80:81]
	s_waitcnt vmcnt(6)
	v_pk_add_f32 v[36:37], v[52:53], v[36:37]
	s_waitcnt vmcnt(5)
	v_pk_add_f32 v[34:35], v[56:57], v[34:35]
	s_waitcnt vmcnt(4)
	v_pk_add_f32 v[32:33], v[60:61], v[32:33]
	s_waitcnt vmcnt(3)
	v_pk_add_f32 v[30:31], v[64:65], v[30:31]
	s_waitcnt vmcnt(2)
	v_pk_add_f32 v[44:45], v[68:69], v[44:45]
	v_pk_add_f32 v[46:47], v[48:49], v[82:83]
	v_pk_add_f32 v[56:57], v[66:67], v[90:91]
	s_waitcnt vmcnt(1)
	v_pk_add_f32 v[42:43], v[72:73], v[42:43]
	v_pk_add_f32 v[60:61], v[74:75], v[94:95]
	s_waitcnt vmcnt(0)
	v_pk_add_f32 v[40:41], v[76:77], v[40:41]
	v_mov_b32_e32 v66, v39
	v_mov_b32_e32 v67, v37
	v_mov_b32_e32 v74, v35
	v_mov_b32_e32 v75, v33
	v_mov_b32_e32 v82, v31
	v_mov_b32_e32 v83, v45
	v_pk_add_f32 v[48:49], v[54:55], v[84:85]
	v_pk_add_f32 v[52:53], v[58:59], v[86:87]
	v_pk_add_f32 v[58:59], v[70:71], v[92:93]
	v_mov_b32_e32 v64, v38
	v_mov_b32_e32 v65, v36
	v_mov_b32_e32 v72, v34
	v_mov_b32_e32 v73, v32
	v_mov_b32_e32 v80, v30
	v_mov_b32_e32 v81, v44
	v_mov_b32_e32 v90, v43
	v_mov_b32_e32 v91, v41
	v_pk_mul_f32 v[66:67], v[66:67], v[66:67]
	v_pk_mul_f32 v[74:75], v[74:75], v[74:75]
	v_pk_mul_f32 v[82:83], v[82:83], v[82:83]
	v_pk_add_f32 v[54:55], v[62:63], v[88:89]
	v_pk_add_f32 v[62:63], v[78:79], v[96:97]
	v_mov_b32_e32 v68, v46
	v_mov_b32_e32 v69, v48
	v_mov_b32_e32 v84, v56
	v_mov_b32_e32 v85, v58
	v_mov_b32_e32 v88, v42
	v_mov_b32_e32 v89, v40
	v_pk_mul_f32 v[90:91], v[90:91], v[90:91]
	v_pk_fma_f32 v[64:65], v[64:65], v[64:65], v[66:67]
	v_pk_fma_f32 v[66:67], v[72:73], v[72:73], v[74:75]
	v_pk_fma_f32 v[72:73], v[80:81], v[80:81], v[82:83]
	v_mov_b32_e32 v70, v47
	v_mov_b32_e32 v71, v49
	v_mov_b32_e32 v76, v52
	v_mov_b32_e32 v77, v54
	v_mov_b32_e32 v86, v57
	v_mov_b32_e32 v87, v59
	v_mov_b32_e32 v92, v60
	v_mov_b32_e32 v93, v62
	v_pk_fma_f32 v[74:75], v[88:89], v[88:89], v[90:91]
	v_pk_fma_f32 v[64:65], v[68:69], v[68:69], v[64:65]
	v_pk_fma_f32 v[68:69], v[84:85], v[84:85], v[72:73]
	v_mov_b32_e32 v78, v53
	v_mov_b32_e32 v79, v55
	v_mov_b32_e32 v94, v61
	v_mov_b32_e32 v95, v63
	v_pk_fma_f32 v[66:67], v[76:77], v[76:77], v[66:67]
	v_pk_fma_f32 v[72:73], v[92:93], v[92:93], v[74:75]
	v_pk_fma_f32 v[64:65], v[70:71], v[70:71], v[64:65]
	v_pk_fma_f32 v[68:69], v[86:87], v[86:87], v[68:69]
	v_pk_fma_f32 v[66:67], v[78:79], v[78:79], v[66:67]
	v_pk_fma_f32 v[70:71], v[94:95], v[94:95], v[72:73]
	v_mov_b32_e32 v72, v68
	v_mov_b32_e32 v73, v64
	v_mov_b32_e32 v64, v69
	v_mov_b32_e32 v68, v70
	v_mov_b32_e32 v69, v66
	v_pk_add_f32 v[64:65], v[72:73], v[64:65]
	v_mov_b32_e32 v66, v71
	v_pk_add_f32 v[64:65], v[64:65], v[68:69]
	s_nop 0
	v_pk_add_f32 v[64:65], v[64:65], v[66:67]
	ds_bpermute_b32 v67, v234, v65
	ds_bpermute_b32 v66, v234, v64
	s_waitcnt lgkmcnt(0)
	v_pk_add_f32 v[64:65], v[64:65], v[66:67]
	ds_bpermute_b32 v67, v235, v65
	ds_bpermute_b32 v66, v235, v64
	s_waitcnt lgkmcnt(0)
	v_pk_add_f32 v[64:65], v[64:65], v[66:67]
	ds_bpermute_b32 v67, v236, v65
	ds_bpermute_b32 v66, v236, v64
	s_waitcnt lgkmcnt(0)
	v_pk_add_f32 v[64:65], v[64:65], v[66:67]
	ds_bpermute_b32 v67, v237, v65
	ds_bpermute_b32 v66, v237, v64
	s_waitcnt lgkmcnt(0)
	v_pk_add_f32 v[64:65], v[64:65], v[66:67]
	ds_bpermute_b32 v67, v238, v65
	ds_bpermute_b32 v66, v238, v64
	s_waitcnt lgkmcnt(0)
	v_pk_add_f32 v[64:65], v[64:65], v[66:67]
	ds_bpermute_b32 v67, v239, v65
	ds_bpermute_b32 v66, v239, v64
	s_waitcnt lgkmcnt(0)
	v_pk_add_f32 v[64:65], v[64:65], v[66:67]
	s_nop 0
	v_pk_fma_f32 v[64:65], v[64:65], s[10:11], v[28:29] op_sel_hi:[1,0,0]
	s_nop 0
	v_mul_f32_e32 v66, 0x4b800000, v65
	v_cmp_gt_f32_e64 s[0:1], s13, v65
	v_mul_f32_e32 v67, 0x4b800000, v64
	v_cmp_gt_f32_e32 vcc, s13, v64
	v_cndmask_b32_e64 v65, v65, v66, s[0:1]
	v_rsq_f32_e32 v65, v65
	v_cndmask_b32_e32 v64, v64, v67, vcc
	v_rsq_f32_e32 v66, v64
	v_mul_f32_e32 v64, 0x45800000, v65
	v_cndmask_b32_e64 v64, v65, v64, s[0:1]
	v_mul_f32_e32 v67, 0x45800000, v66
	v_cndmask_b32_e32 v66, v66, v67, vcc
	v_pk_mul_f32 v[38:39], v[38:39], v[64:65] op_sel_hi:[1,0]
	v_pk_mul_f32 v[46:47], v[46:47], v[64:65] op_sel_hi:[1,0]
	v_pk_mul_f32 v[68:69], v[36:37], v[64:65] op_sel_hi:[1,0]
	v_pk_mul_f32 v[36:37], v[48:49], v[64:65] op_sel_hi:[1,0]
	v_pk_mul_f32 v[48:49], v[34:35], v[64:65] op_sel_hi:[1,0]
	v_pk_mul_f32 v[52:53], v[52:53], v[64:65] op_sel_hi:[1,0]
	v_pk_mul_f32 v[70:71], v[32:33], v[64:65] op_sel_hi:[1,0]
	v_pk_mul_f32 v[54:55], v[54:55], v[64:65] op_sel_hi:[1,0]
	v_pk_mul_f32 v[64:65], v[30:31], v[66:67] op_sel_hi:[1,0]
	v_pk_mul_f32 v[56:57], v[56:57], v[66:67] op_sel_hi:[1,0]
	v_pk_mul_f32 v[72:73], v[44:45], v[66:67] op_sel_hi:[1,0]
	v_pk_mul_f32 v[58:59], v[58:59], v[66:67] op_sel_hi:[1,0]
	v_pk_mul_f32 v[74:75], v[42:43], v[66:67] op_sel_hi:[1,0]
	v_pk_mul_f32 v[60:61], v[60:61], v[66:67] op_sel_hi:[1,0]
	v_pk_mul_f32 v[76:77], v[40:41], v[66:67] op_sel_hi:[1,0]
	v_pk_mul_f32 v[62:63], v[62:63], v[66:67] op_sel_hi:[1,0]
	v_pk_mul_f32 v[32:33], v[14:15], v[46:47]
	v_pk_mul_f32 v[30:31], v[12:13], v[38:39]
	v_pk_mul_f32 v[36:37], v[10:11], v[36:37]
	v_pk_mul_f32 v[34:35], v[8:9], v[68:69]
	v_pk_mul_f32 v[40:41], v[6:7], v[52:53]
	v_pk_mul_f32 v[38:39], v[4:5], v[48:49]
	v_pk_mul_f32 v[44:45], v[2:3], v[54:55]
	v_pk_mul_f32 v[42:43], v[0:1], v[70:71]
	v_pk_mul_f32 v[14:15], v[14:15], v[56:57]
	v_pk_mul_f32 v[12:13], v[12:13], v[64:65]
	v_pk_mul_f32 v[10:11], v[10:11], v[58:59]
	v_pk_mul_f32 v[8:9], v[8:9], v[72:73]
	v_pk_mul_f32 v[6:7], v[6:7], v[60:61]
	v_pk_mul_f32 v[4:5], v[4:5], v[74:75]
	v_pk_mul_f32 v[2:3], v[2:3], v[62:63]
	v_pk_mul_f32 v[0:1], v[0:1], v[76:77]
	global_store_dwordx4 v[22:23], v[30:33], off offset:-4096 nt
	global_store_dwordx4 v[22:23], v[34:37], off offset:-3072 nt
	global_store_dwordx4 v[22:23], v[38:41], off offset:-2048 nt
	global_store_dwordx4 v[22:23], v[42:45], off offset:-1024 nt
	global_store_dwordx4 v[22:23], v[12:15], off nt
	global_store_dwordx4 v[22:23], v[8:11], off offset:1024 nt
	global_store_dwordx4 v[22:23], v[4:7], off offset:2048 nt
	global_store_dwordx4 v[22:23], v[0:3], off offset:3072 nt
	v_lshl_add_u64 v[22:23], v[22:23], 0, s[4:5]
	s_andn2_b64 exec, exec, s[8:9]
	s_cbranch_execnz .LBB0_1051
	s_branch .Lp6_passend
.Lp6_skip:
	v_add_u32_e32 v16, s11, v16
	v_cmp_lt_i32_e32 vcc, s14, v16
	s_or_b64 s[8:9], vcc, s[8:9]
	v_lshl_add_u64 v[24:25], v[24:25], 0, s[6:7]
	v_lshl_add_u64 v[26:27], v[26:27], 0, s[2:3]
	v_lshl_add_u64 v[22:23], v[22:23], 0, s[4:5]
	s_andn2_b64 exec, exec, s[8:9]
	s_cbranch_execnz .LBB0_1051
.Lp6_passend:
	s_mov_b64 exec, -1
	s_cmp_eq_u32 s98, 1
	s_cbranch_scc1 .LBB0_1052
	s_cmp_eq_u32 s100, -1
	s_cbranch_scc1 .LBB0_1052
	s_mov_b32 s98, 1
	v_readlane_b32 s0, v252, 35
	v_readlane_b32 s1, v252, 36
	s_and_b64 vcc, exec, s[0:1]
	s_cbranch_vccnz .Lp6_gotB
	v_readlane_b32 s2, v252, 25
	v_readlane_b32 s3, v252, 26
	v_mov_b32_e32 v0, 0
	s_mov_b32 s9, 0
	s_nop 2
.Lp6_pollB:
	global_load_dword v1, v0, s[2:3] offset:768 sc1
	s_waitcnt vmcnt(0)
	v_readfirstlane_b32 s4, v1
	s_cmp_ge_u32 s4, 8
	s_cbranch_scc1 .Lp6_okB
	s_sleep 2
	s_add_i32 s9, s9, 1
	s_cmp_lt_u32 s9, 0x8000
	s_cbranch_scc1 .Lp6_pollB

.Lp6_gotB:
	s_barrier
	s_branch .Lp6_pass
